# attention phase set-up (smax + bias table): 8 rpb loads per lane in flight instead of 16 serialized round trips, same values; on top of fold_uw MFMA + FFT-B rewrite + phase-0 pipelining
# speedup vs baseline: 1.0246x; 1.0025x over previous
.LBB0_378:
	s_cmp_lt_i32 s82, 4
	s_cselect_b64 s[0:1], -1, 0
	s_waitcnt lgkmcnt(0)
	s_and_b64 s[44:45], s[0:1], s[2:3]
	s_andn2_b64 vcc, exec, s[44:45]
	s_cbranch_vccnz .LBB0_509
	s_and_b32 s0, s33, 1
	s_cmp_eq_u32 s0, 0
	s_cselect_b64 s[48:49], -1, 0
	s_cmp_eq_u32 s0, 1
	s_cselect_b64 s[0:1], -1, 0
	s_movk_i32 s52, 0x100
	s_movk_i32 s50, 0x80
	s_mov_b32 s74, 0
	s_and_b64 vcc, exec, s[0:1]
	s_cbranch_vccz .LBB0_386
	s_mul_i32 s4, s92, 0x1d1
	v_lshrrev_b32_e32 v0, 5, v180
	v_and_b32_e32 v7, 31, v180
	v_mul_u32_u24_e32 v0, 31, v0
	v_add3_u32 v0, s4, v0, v7
	v_lshlrev_b32_e32 v0, 2, v0
	v_cmp_ne_u32_e32 vcc, 31, v7
	v_lshlrev_b32_e32 v16, 2, v180
	v_mov_b32_e32 v20, 0
	v_mov_b32_e32 v21, 0
	v_mov_b32_e32 v22, 0
	v_mov_b32_e32 v23, 0
	v_mov_b32_e32 v24, 0
	v_mov_b32_e32 v25, 0
	v_mov_b32_e32 v26, 0
	v_mov_b32_e32 v27, 0
	s_waitcnt lgkmcnt(0)
	global_load_dword v2, v16, s[40:41]
	global_load_dword v3, v16, s[42:43]
	s_mov_b64 s[2:3], exec
	v_cmp_gt_u32_e64 s[0:1], 32, v180
	s_and_b64 exec, exec, vcc
	global_load_dword v20, v0, s[46:47]
	global_load_dword v21, v0, s[46:47] offset:248
	global_load_dword v22, v0, s[46:47] offset:496
	global_load_dword v23, v0, s[46:47] offset:744
	global_load_dword v24, v0, s[46:47] offset:992
	global_load_dword v25, v0, s[46:47] offset:1240
	global_load_dword v26, v0, s[46:47] offset:1488
	s_and_b64 exec, exec, s[0:1]
	global_load_dword v27, v0, s[46:47] offset:1736
	s_mov_b64 exec, s[2:3]
	v_xor_b32_e32 v8, 1, v180
	v_lshlrev_b32_e32 v8, 2, v8
	v_xor_b32_e32 v9, 2, v180
	v_lshlrev_b32_e32 v9, 2, v9
	v_xor_b32_e32 v10, 4, v180
	v_lshlrev_b32_e32 v10, 2, v10
	v_xor_b32_e32 v11, 8, v180
	v_lshlrev_b32_e32 v11, 2, v11
	v_xor_b32_e32 v137, 16, v180
	v_lshlrev_b32_e32 v137, 2, v137
	v_xor_b32_e32 v138, 32, v180
	v_lshlrev_b32_e32 v138, 2, v138
	s_mul_i32 s5, s92, 0x780
	v_add_u32_e32 v16, s5, v16
	v_add_u32_e32 v16, 0xa000, v16
	s_waitcnt vmcnt(8)
	v_max_f32_e64 v5, |v2|, |v2|
	v_max_f32_e64 v6, |v3|, |v3|
	s_waitcnt vmcnt(0)
	v_max_f32_e64 v1, |v20|, |v21|
	v_max_f32_e64 v4, |v22|, |v23|
	v_max_f32_e64 v12, |v24|, |v25|
	v_max_f32_e64 v13, |v26|, |v27|
	v_max_f32_e32 v1, v1, v4
	v_max_f32_e32 v12, v12, v13
	v_max_f32_e32 v1, v1, v12
	ds_bpermute_b32 v12, v8, v1
	ds_bpermute_b32 v13, v8, v5
	ds_bpermute_b32 v14, v8, v6
	s_waitcnt lgkmcnt(0)
	v_max_f32_e32 v1, v1, v12
	v_max_f32_e32 v5, v5, v13
	v_max_f32_e32 v6, v6, v14
	ds_bpermute_b32 v12, v9, v1
	ds_bpermute_b32 v13, v9, v5
	ds_bpermute_b32 v14, v9, v6
	s_waitcnt lgkmcnt(0)
	v_max_f32_e32 v1, v1, v12
	v_max_f32_e32 v5, v5, v13
	v_max_f32_e32 v6, v6, v14
	ds_bpermute_b32 v12, v10, v1
	ds_bpermute_b32 v13, v10, v5
	ds_bpermute_b32 v14, v10, v6
	s_waitcnt lgkmcnt(0)
	v_max_f32_e32 v1, v1, v12
	v_max_f32_e32 v5, v5, v13
	v_max_f32_e32 v6, v6, v14
	ds_bpermute_b32 v12, v11, v1
	ds_bpermute_b32 v13, v11, v5
	ds_bpermute_b32 v14, v11, v6
	s_waitcnt lgkmcnt(0)
	v_max_f32_e32 v1, v1, v12
	v_max_f32_e32 v5, v5, v13
	v_max_f32_e32 v6, v6, v14
	ds_bpermute_b32 v12, v137, v1
	ds_bpermute_b32 v13, v137, v5
	ds_bpermute_b32 v14, v137, v6
	s_waitcnt lgkmcnt(0)
	v_max_f32_e32 v1, v1, v12
	v_max_f32_e32 v5, v5, v13
	v_max_f32_e32 v6, v6, v14
	ds_bpermute_b32 v12, v138, v1
	ds_bpermute_b32 v13, v138, v5
	ds_bpermute_b32 v14, v138, v6
	s_waitcnt lgkmcnt(0)
	v_max_f32_e32 v1, v1, v12
	v_max_f32_e32 v5, v5, v13
	v_max_f32_e32 v6, v6, v14
	v_mul_f32_e32 v5, 0x41000000, v5
	v_fmac_f32_e32 v1, v6, v5
	v_mov_b32_e32 v15, 0xf149f2ca
	v_sub_f32_e32 v12, v20, v1
	v_mul_f32_e32 v12, 0x3fb8aa3b, v12
	v_cndmask_b32_e32 v12, v15, v12, vcc
	ds_write_b32 v16, v12
	v_sub_f32_e32 v12, v21, v1
	v_mul_f32_e32 v12, 0x3fb8aa3b, v12
	v_cndmask_b32_e32 v12, v15, v12, vcc
	ds_write_b32 v16, v12 offset:256
	v_sub_f32_e32 v12, v22, v1
	v_mul_f32_e32 v12, 0x3fb8aa3b, v12
	v_cndmask_b32_e32 v12, v15, v12, vcc
	ds_write_b32 v16, v12 offset:512
	v_sub_f32_e32 v12, v23, v1
	v_mul_f32_e32 v12, 0x3fb8aa3b, v12
	v_cndmask_b32_e32 v12, v15, v12, vcc
	ds_write_b32 v16, v12 offset:768
	v_sub_f32_e32 v12, v24, v1
	v_mul_f32_e32 v12, 0x3fb8aa3b, v12
	v_cndmask_b32_e32 v12, v15, v12, vcc
	ds_write_b32 v16, v12 offset:1024
	v_sub_f32_e32 v12, v25, v1
	v_mul_f32_e32 v12, 0x3fb8aa3b, v12
	v_cndmask_b32_e32 v12, v15, v12, vcc
	ds_write_b32 v16, v12 offset:1280
	v_sub_f32_e32 v12, v26, v1
	v_mul_f32_e32 v12, 0x3fb8aa3b, v12
	v_cndmask_b32_e32 v12, v15, v12, vcc
	ds_write_b32 v16, v12 offset:1536
	v_sub_f32_e32 v12, v27, v1
	v_mul_f32_e32 v12, 0x3fb8aa3b, v12
	v_cndmask_b32_e32 v12, v15, v12, vcc
	s_and_b64 exec, exec, s[0:1]
	ds_write_b32 v16, v12 offset:1792
	s_mov_b64 exec, s[2:3]
	s_mov_b64 s[2:3], -1
	s_branch .LBB0_387

.LBB0_464:
	s_andn2_b64 vcc, exec, s[48:49]
	s_cbranch_vccnz .LBB0_509
	s_mul_i32 s4, s92, 0x1d1
	v_lshrrev_b32_e32 v0, 5, v180
	v_and_b32_e32 v7, 31, v180
	v_mul_u32_u24_e32 v0, 31, v0
	v_add3_u32 v0, s4, v0, v7
	v_lshlrev_b32_e32 v0, 2, v0
	v_cmp_ne_u32_e32 vcc, 31, v7
	v_lshlrev_b32_e32 v16, 2, v180
	v_mov_b32_e32 v20, 0
	v_mov_b32_e32 v21, 0
	v_mov_b32_e32 v22, 0
	v_mov_b32_e32 v23, 0
	v_mov_b32_e32 v24, 0
	v_mov_b32_e32 v25, 0
	v_mov_b32_e32 v26, 0
	v_mov_b32_e32 v27, 0
	s_waitcnt lgkmcnt(0)
	global_load_dword v2, v16, s[40:41]
	global_load_dword v3, v16, s[42:43]
	s_mov_b64 s[2:3], exec
	v_cmp_gt_u32_e64 s[0:1], 32, v180
	s_and_b64 exec, exec, vcc
	global_load_dword v20, v0, s[46:47]
	global_load_dword v21, v0, s[46:47] offset:248
	global_load_dword v22, v0, s[46:47] offset:496
	global_load_dword v23, v0, s[46:47] offset:744
	global_load_dword v24, v0, s[46:47] offset:992
	global_load_dword v25, v0, s[46:47] offset:1240
	global_load_dword v26, v0, s[46:47] offset:1488
	s_and_b64 exec, exec, s[0:1]
	global_load_dword v27, v0, s[46:47] offset:1736
	s_mov_b64 exec, s[2:3]
	v_xor_b32_e32 v8, 1, v180
	v_lshlrev_b32_e32 v8, 2, v8
	v_xor_b32_e32 v9, 2, v180
	v_lshlrev_b32_e32 v9, 2, v9
	v_xor_b32_e32 v10, 4, v180
	v_lshlrev_b32_e32 v10, 2, v10
	v_xor_b32_e32 v11, 8, v180
	v_lshlrev_b32_e32 v11, 2, v11
	v_xor_b32_e32 v137, 16, v180
	v_lshlrev_b32_e32 v137, 2, v137
	v_xor_b32_e32 v138, 32, v180
	v_lshlrev_b32_e32 v138, 2, v138
	s_mul_i32 s5, s92, 0x780
	v_add_u32_e32 v16, s5, v16
	v_add_u32_e32 v16, 0xa000, v16
	s_waitcnt vmcnt(8)
	v_max_f32_e64 v5, |v2|, |v2|
	v_max_f32_e64 v6, |v3|, |v3|
	s_waitcnt vmcnt(0)
	v_max_f32_e64 v1, |v20|, |v21|
	v_max_f32_e64 v4, |v22|, |v23|
	v_max_f32_e64 v12, |v24|, |v25|
	v_max_f32_e64 v13, |v26|, |v27|
	v_max_f32_e32 v1, v1, v4
	v_max_f32_e32 v12, v12, v13
	v_max_f32_e32 v1, v1, v12
	ds_bpermute_b32 v12, v8, v1
	ds_bpermute_b32 v13, v8, v5
	ds_bpermute_b32 v14, v8, v6
	s_waitcnt lgkmcnt(0)
	v_max_f32_e32 v1, v1, v12
	v_max_f32_e32 v5, v5, v13
	v_max_f32_e32 v6, v6, v14
	ds_bpermute_b32 v12, v9, v1
	ds_bpermute_b32 v13, v9, v5
	ds_bpermute_b32 v14, v9, v6
	s_waitcnt lgkmcnt(0)
	v_max_f32_e32 v1, v1, v12
	v_max_f32_e32 v5, v5, v13
	v_max_f32_e32 v6, v6, v14
	ds_bpermute_b32 v12, v10, v1
	ds_bpermute_b32 v13, v10, v5
	ds_bpermute_b32 v14, v10, v6
	s_waitcnt lgkmcnt(0)
	v_max_f32_e32 v1, v1, v12
	v_max_f32_e32 v5, v5, v13
	v_max_f32_e32 v6, v6, v14
	ds_bpermute_b32 v12, v11, v1
	ds_bpermute_b32 v13, v11, v5
	ds_bpermute_b32 v14, v11, v6
	s_waitcnt lgkmcnt(0)
	v_max_f32_e32 v1, v1, v12
	v_max_f32_e32 v5, v5, v13
	v_max_f32_e32 v6, v6, v14
	ds_bpermute_b32 v12, v137, v1
	ds_bpermute_b32 v13, v137, v5
	ds_bpermute_b32 v14, v137, v6
	s_waitcnt lgkmcnt(0)
	v_max_f32_e32 v1, v1, v12
	v_max_f32_e32 v5, v5, v13
	v_max_f32_e32 v6, v6, v14
	ds_bpermute_b32 v12, v138, v1
	ds_bpermute_b32 v13, v138, v5
	ds_bpermute_b32 v14, v138, v6
	s_waitcnt lgkmcnt(0)
	v_max_f32_e32 v1, v1, v12
	v_max_f32_e32 v5, v5, v13
	v_max_f32_e32 v6, v6, v14
	v_mul_f32_e32 v5, 0x41000000, v5
	v_fmac_f32_e32 v1, v6, v5
	v_mov_b32_e32 v15, 0xf149f2ca
	v_sub_f32_e32 v12, v20, v1
	v_mul_f32_e32 v12, 0x3fb8aa3b, v12
	v_cndmask_b32_e32 v12, v15, v12, vcc
	ds_write_b32 v16, v12
	v_sub_f32_e32 v12, v21, v1
	v_mul_f32_e32 v12, 0x3fb8aa3b, v12
	v_cndmask_b32_e32 v12, v15, v12, vcc
	ds_write_b32 v16, v12 offset:256
	v_sub_f32_e32 v12, v22, v1
	v_mul_f32_e32 v12, 0x3fb8aa3b, v12
	v_cndmask_b32_e32 v12, v15, v12, vcc
	ds_write_b32 v16, v12 offset:512
	v_sub_f32_e32 v12, v23, v1
	v_mul_f32_e32 v12, 0x3fb8aa3b, v12
	v_cndmask_b32_e32 v12, v15, v12, vcc
	ds_write_b32 v16, v12 offset:768
	v_sub_f32_e32 v12, v24, v1
	v_mul_f32_e32 v12, 0x3fb8aa3b, v12
	v_cndmask_b32_e32 v12, v15, v12, vcc
	ds_write_b32 v16, v12 offset:1024
	v_sub_f32_e32 v12, v25, v1
	v_mul_f32_e32 v12, 0x3fb8aa3b, v12
	v_cndmask_b32_e32 v12, v15, v12, vcc
	ds_write_b32 v16, v12 offset:1280
	v_sub_f32_e32 v12, v26, v1
	v_mul_f32_e32 v12, 0x3fb8aa3b, v12
	v_cndmask_b32_e32 v12, v15, v12, vcc
	ds_write_b32 v16, v12 offset:1536
	v_sub_f32_e32 v12, v27, v1
	v_mul_f32_e32 v12, 0x3fb8aa3b, v12
	v_cndmask_b32_e32 v12, v15, v12, vcc
	s_and_b64 exec, exec, s[0:1]
	ds_write_b32 v16, v12 offset:1792
	s_mov_b64 exec, s[2:3]
	s_mov_b64 s[2:3], -1

.LBB0_563:
	s_cmp_lt_i32 s82, 5
	s_cselect_b64 s[2:3], -1, 0
	s_and_b64 s[44:45], s[2:3], s[0:1]
	s_andn2_b64 vcc, exec, s[44:45]
	s_cbranch_vccnz .LBB0_710
	s_and_b32 s0, s33, 1
	s_cmp_eq_u32 s0, 0
	s_cselect_b64 s[48:49], -1, 0
	s_cmp_eq_u32 s0, 1
	s_cselect_b64 s[0:1], -1, 0
	s_movk_i32 s50, 0x80
	s_and_b64 vcc, exec, s[0:1]
	s_mul_i32 s97, s92, 0x1d1
	s_cbranch_vccz .LBB0_571
	v_lshrrev_b32_e32 v0, 5, v180
	v_and_b32_e32 v7, 31, v180
	v_mul_u32_u24_e32 v0, 31, v0
	v_add3_u32 v0, s97, v0, v7
	v_lshlrev_b32_e32 v0, 2, v0
	v_cmp_ne_u32_e32 vcc, 31, v7
	v_lshlrev_b32_e32 v16, 2, v180
	v_mov_b32_e32 v20, 0
	v_mov_b32_e32 v21, 0
	v_mov_b32_e32 v22, 0
	v_mov_b32_e32 v23, 0
	v_mov_b32_e32 v24, 0
	v_mov_b32_e32 v25, 0
	v_mov_b32_e32 v26, 0
	v_mov_b32_e32 v27, 0
	s_waitcnt lgkmcnt(0)
	global_load_dword v2, v16, s[40:41]
	global_load_dword v3, v16, s[42:43]
	s_mov_b64 s[2:3], exec
	v_cmp_gt_u32_e64 s[0:1], 32, v180
	s_and_b64 exec, exec, vcc
	global_load_dword v20, v0, s[46:47]
	global_load_dword v21, v0, s[46:47] offset:248
	global_load_dword v22, v0, s[46:47] offset:496
	global_load_dword v23, v0, s[46:47] offset:744
	global_load_dword v24, v0, s[46:47] offset:992
	global_load_dword v25, v0, s[46:47] offset:1240
	global_load_dword v26, v0, s[46:47] offset:1488
	s_and_b64 exec, exec, s[0:1]
	global_load_dword v27, v0, s[46:47] offset:1736
	s_mov_b64 exec, s[2:3]
	v_xor_b32_e32 v8, 1, v180
	v_lshlrev_b32_e32 v8, 2, v8
	v_xor_b32_e32 v9, 2, v180
	v_lshlrev_b32_e32 v9, 2, v9
	v_xor_b32_e32 v10, 4, v180
	v_lshlrev_b32_e32 v10, 2, v10
	v_xor_b32_e32 v11, 8, v180
	v_lshlrev_b32_e32 v11, 2, v11
	v_xor_b32_e32 v138, 16, v180
	v_lshlrev_b32_e32 v138, 2, v138
	v_xor_b32_e32 v139, 32, v180
	v_lshlrev_b32_e32 v139, 2, v139
	s_mul_i32 s5, s92, 0x780
	v_add_u32_e32 v16, s5, v16
	v_add_u32_e32 v16, 0xa000, v16
	s_waitcnt vmcnt(8)
	v_max_f32_e64 v5, |v2|, |v2|
	v_max_f32_e64 v6, |v3|, |v3|
	s_waitcnt vmcnt(0)
	v_max_f32_e64 v1, |v20|, |v21|
	v_max_f32_e64 v4, |v22|, |v23|
	v_max_f32_e64 v12, |v24|, |v25|
	v_max_f32_e64 v13, |v26|, |v27|
	v_max_f32_e32 v1, v1, v4
	v_max_f32_e32 v12, v12, v13
	v_max_f32_e32 v1, v1, v12
	ds_bpermute_b32 v12, v8, v1
	ds_bpermute_b32 v13, v8, v5
	ds_bpermute_b32 v14, v8, v6
	s_waitcnt lgkmcnt(0)
	v_max_f32_e32 v1, v1, v12
	v_max_f32_e32 v5, v5, v13
	v_max_f32_e32 v6, v6, v14
	ds_bpermute_b32 v12, v9, v1
	ds_bpermute_b32 v13, v9, v5
	ds_bpermute_b32 v14, v9, v6
	s_waitcnt lgkmcnt(0)
	v_max_f32_e32 v1, v1, v12
	v_max_f32_e32 v5, v5, v13
	v_max_f32_e32 v6, v6, v14
	ds_bpermute_b32 v12, v10, v1
	ds_bpermute_b32 v13, v10, v5
	ds_bpermute_b32 v14, v10, v6
	s_waitcnt lgkmcnt(0)
	v_max_f32_e32 v1, v1, v12
	v_max_f32_e32 v5, v5, v13
	v_max_f32_e32 v6, v6, v14
	ds_bpermute_b32 v12, v11, v1
	ds_bpermute_b32 v13, v11, v5
	ds_bpermute_b32 v14, v11, v6
	s_waitcnt lgkmcnt(0)
	v_max_f32_e32 v1, v1, v12
	v_max_f32_e32 v5, v5, v13
	v_max_f32_e32 v6, v6, v14
	ds_bpermute_b32 v12, v138, v1
	ds_bpermute_b32 v13, v138, v5
	ds_bpermute_b32 v14, v138, v6
	s_waitcnt lgkmcnt(0)
	v_max_f32_e32 v1, v1, v12
	v_max_f32_e32 v5, v5, v13
	v_max_f32_e32 v6, v6, v14
	ds_bpermute_b32 v12, v139, v1
	ds_bpermute_b32 v13, v139, v5
	ds_bpermute_b32 v14, v139, v6
	s_waitcnt lgkmcnt(0)
	v_max_f32_e32 v1, v1, v12
	v_max_f32_e32 v5, v5, v13
	v_max_f32_e32 v6, v6, v14
	v_mul_f32_e32 v5, 0x41000000, v5
	v_fmac_f32_e32 v1, v6, v5
	v_mov_b32_e32 v15, 0xf149f2ca
	v_sub_f32_e32 v12, v20, v1
	v_mul_f32_e32 v12, 0x3fb8aa3b, v12
	v_cndmask_b32_e32 v12, v15, v12, vcc
	ds_write_b32 v16, v12
	v_sub_f32_e32 v12, v21, v1
	v_mul_f32_e32 v12, 0x3fb8aa3b, v12
	v_cndmask_b32_e32 v12, v15, v12, vcc
	ds_write_b32 v16, v12 offset:256
	v_sub_f32_e32 v12, v22, v1
	v_mul_f32_e32 v12, 0x3fb8aa3b, v12
	v_cndmask_b32_e32 v12, v15, v12, vcc
	ds_write_b32 v16, v12 offset:512
	v_sub_f32_e32 v12, v23, v1
	v_mul_f32_e32 v12, 0x3fb8aa3b, v12
	v_cndmask_b32_e32 v12, v15, v12, vcc
	ds_write_b32 v16, v12 offset:768
	v_sub_f32_e32 v12, v24, v1
	v_mul_f32_e32 v12, 0x3fb8aa3b, v12
	v_cndmask_b32_e32 v12, v15, v12, vcc
	ds_write_b32 v16, v12 offset:1024
	v_sub_f32_e32 v12, v25, v1
	v_mul_f32_e32 v12, 0x3fb8aa3b, v12
	v_cndmask_b32_e32 v12, v15, v12, vcc
	ds_write_b32 v16, v12 offset:1280
	v_sub_f32_e32 v12, v26, v1
	v_mul_f32_e32 v12, 0x3fb8aa3b, v12
	v_cndmask_b32_e32 v12, v15, v12, vcc
	ds_write_b32 v16, v12 offset:1536
	v_sub_f32_e32 v12, v27, v1
	v_mul_f32_e32 v12, 0x3fb8aa3b, v12
	v_cndmask_b32_e32 v12, v15, v12, vcc
	s_and_b64 exec, exec, s[0:1]
	ds_write_b32 v16, v12 offset:1792
	s_mov_b64 exec, s[2:3]
	s_mov_b64 s[2:3], -1
	s_branch .LBB0_572

.LBB0_665:
	s_andn2_b64 vcc, exec, s[48:49]
	s_cbranch_vccnz .LBB0_710
	v_lshrrev_b32_e32 v0, 5, v180
	v_and_b32_e32 v7, 31, v180
	v_mul_u32_u24_e32 v0, 31, v0
	v_add3_u32 v0, s97, v0, v7
	v_lshlrev_b32_e32 v0, 2, v0
	v_cmp_ne_u32_e32 vcc, 31, v7
	v_lshlrev_b32_e32 v16, 2, v180
	v_mov_b32_e32 v20, 0
	v_mov_b32_e32 v21, 0
	v_mov_b32_e32 v22, 0
	v_mov_b32_e32 v23, 0
	v_mov_b32_e32 v24, 0
	v_mov_b32_e32 v25, 0
	v_mov_b32_e32 v26, 0
	v_mov_b32_e32 v27, 0
	s_waitcnt lgkmcnt(0)
	global_load_dword v2, v16, s[40:41]
	global_load_dword v3, v16, s[42:43]
	s_mov_b64 s[2:3], exec
	v_cmp_gt_u32_e64 s[0:1], 32, v180
	s_and_b64 exec, exec, vcc
	global_load_dword v20, v0, s[46:47]
	global_load_dword v21, v0, s[46:47] offset:248
	global_load_dword v22, v0, s[46:47] offset:496
	global_load_dword v23, v0, s[46:47] offset:744
	global_load_dword v24, v0, s[46:47] offset:992
	global_load_dword v25, v0, s[46:47] offset:1240
	global_load_dword v26, v0, s[46:47] offset:1488
	s_and_b64 exec, exec, s[0:1]
	global_load_dword v27, v0, s[46:47] offset:1736
	s_mov_b64 exec, s[2:3]
	v_xor_b32_e32 v8, 1, v180
	v_lshlrev_b32_e32 v8, 2, v8
	v_xor_b32_e32 v9, 2, v180
	v_lshlrev_b32_e32 v9, 2, v9
	v_xor_b32_e32 v10, 4, v180
	v_lshlrev_b32_e32 v10, 2, v10
	v_xor_b32_e32 v11, 8, v180
	v_lshlrev_b32_e32 v11, 2, v11
	v_xor_b32_e32 v138, 16, v180
	v_lshlrev_b32_e32 v138, 2, v138
	v_xor_b32_e32 v139, 32, v180
	v_lshlrev_b32_e32 v139, 2, v139
	s_mul_i32 s5, s92, 0x780
	v_add_u32_e32 v16, s5, v16
	v_add_u32_e32 v16, 0xa000, v16
	s_waitcnt vmcnt(8)
	v_max_f32_e64 v5, |v2|, |v2|
	v_max_f32_e64 v6, |v3|, |v3|
	s_waitcnt vmcnt(0)
	v_max_f32_e64 v1, |v20|, |v21|
	v_max_f32_e64 v4, |v22|, |v23|
	v_max_f32_e64 v12, |v24|, |v25|
	v_max_f32_e64 v13, |v26|, |v27|
	v_max_f32_e32 v1, v1, v4
	v_max_f32_e32 v12, v12, v13
	v_max_f32_e32 v1, v1, v12
	ds_bpermute_b32 v12, v8, v1
	ds_bpermute_b32 v13, v8, v5
	ds_bpermute_b32 v14, v8, v6
	s_waitcnt lgkmcnt(0)
	v_max_f32_e32 v1, v1, v12
	v_max_f32_e32 v5, v5, v13
	v_max_f32_e32 v6, v6, v14
	ds_bpermute_b32 v12, v9, v1
	ds_bpermute_b32 v13, v9, v5
	ds_bpermute_b32 v14, v9, v6
	s_waitcnt lgkmcnt(0)
	v_max_f32_e32 v1, v1, v12
	v_max_f32_e32 v5, v5, v13
	v_max_f32_e32 v6, v6, v14
	ds_bpermute_b32 v12, v10, v1
	ds_bpermute_b32 v13, v10, v5
	ds_bpermute_b32 v14, v10, v6
	s_waitcnt lgkmcnt(0)
	v_max_f32_e32 v1, v1, v12
	v_max_f32_e32 v5, v5, v13
	v_max_f32_e32 v6, v6, v14
	ds_bpermute_b32 v12, v11, v1
	ds_bpermute_b32 v13, v11, v5
	ds_bpermute_b32 v14, v11, v6
	s_waitcnt lgkmcnt(0)
	v_max_f32_e32 v1, v1, v12
	v_max_f32_e32 v5, v5, v13
	v_max_f32_e32 v6, v6, v14
	ds_bpermute_b32 v12, v138, v1
	ds_bpermute_b32 v13, v138, v5
	ds_bpermute_b32 v14, v138, v6
	s_waitcnt lgkmcnt(0)
	v_max_f32_e32 v1, v1, v12
	v_max_f32_e32 v5, v5, v13
	v_max_f32_e32 v6, v6, v14
	ds_bpermute_b32 v12, v139, v1
	ds_bpermute_b32 v13, v139, v5
	ds_bpermute_b32 v14, v139, v6
	s_waitcnt lgkmcnt(0)
	v_max_f32_e32 v1, v1, v12
	v_max_f32_e32 v5, v5, v13
	v_max_f32_e32 v6, v6, v14
	v_mul_f32_e32 v5, 0x41000000, v5
	v_fmac_f32_e32 v1, v6, v5
	v_mov_b32_e32 v15, 0xf149f2ca
	v_sub_f32_e32 v12, v20, v1
	v_mul_f32_e32 v12, 0x3fb8aa3b, v12
	v_cndmask_b32_e32 v12, v15, v12, vcc
	ds_write_b32 v16, v12
	v_sub_f32_e32 v12, v21, v1
	v_mul_f32_e32 v12, 0x3fb8aa3b, v12
	v_cndmask_b32_e32 v12, v15, v12, vcc
	ds_write_b32 v16, v12 offset:256
	v_sub_f32_e32 v12, v22, v1
	v_mul_f32_e32 v12, 0x3fb8aa3b, v12
	v_cndmask_b32_e32 v12, v15, v12, vcc
	ds_write_b32 v16, v12 offset:512
	v_sub_f32_e32 v12, v23, v1
	v_mul_f32_e32 v12, 0x3fb8aa3b, v12
	v_cndmask_b32_e32 v12, v15, v12, vcc
	ds_write_b32 v16, v12 offset:768
	v_sub_f32_e32 v12, v24, v1
	v_mul_f32_e32 v12, 0x3fb8aa3b, v12
	v_cndmask_b32_e32 v12, v15, v12, vcc
	ds_write_b32 v16, v12 offset:1024
	v_sub_f32_e32 v12, v25, v1
	v_mul_f32_e32 v12, 0x3fb8aa3b, v12
	v_cndmask_b32_e32 v12, v15, v12, vcc
	ds_write_b32 v16, v12 offset:1280
	v_sub_f32_e32 v12, v26, v1
	v_mul_f32_e32 v12, 0x3fb8aa3b, v12
	v_cndmask_b32_e32 v12, v15, v12, vcc
	ds_write_b32 v16, v12 offset:1536
	v_sub_f32_e32 v12, v27, v1
	v_mul_f32_e32 v12, 0x3fb8aa3b, v12
	v_cndmask_b32_e32 v12, v15, v12, vcc
	s_and_b64 exec, exec, s[0:1]
	ds_write_b32 v16, v12 offset:1792
	s_mov_b64 exec, s[2:3]
	s_mov_b64 s[2:3], -1
